# stack1 + P1 weight-conversion counted waits (dummy loads on no-next-item paths)
# baseline (speedup 1.0000x reference)
; __device__ __forceinline__ void p0_item_decode(const Params& p, int it, const float*& W, int& ld, int& nblk, int& K, bf16_t*& WT, bool& uzmap, int& r) {
;     r = it; uzmap = false;
;     if (r < P0_I0) { W = p.w_in0; ld = LDW0; nblk = N1 / 32; K = DM; WT = (bf16_t*)(p.ws + WS_W0T); return; } r -= P0_I0;
;     if (r < P0_I1) { W = p.w_out0; ld = DM; nblk = DM / 32; K = DM; WT = (bf16_t*)(p.ws + WS_WO0T); return; } r -= P0_I1;
;     if (r < P0_I2) { W = p.w_in1; ld = N3; nblk = N3 / 32; K = DM; WT = (bf16_t*)(p.ws + WS_W1T); uzmap = true; return; } r -= P0_I2;
;     W = p.w_out1; ld = DM; nblk = DM / 32; K = CW; WT = (bf16_t*)(p.ws + WS_WO1T);
; }
; __device__ __forceinline__ void p0_item_load(const Params& p, int it, float (&t)[32], int lane) {
;     const float* W; int ld, nblk, K, r; bf16_t* WT; bool uz; p0_item_decode(p, it, W, ld, nblk, K, WT, uz, r);
;     const int kb = r / nblk, nb = r % nblk, k0 = 64 * kb, n0 = 32 * nb;
;     const float* src = W + (size_t)(k0 + (lane >> 5)) * ld + n0 + (lane & 31);
; #pragma unroll
;     for (int i = 0; i < 32; ++i) t[i] = __builtin_nontemporal_load(src + (size_t)(2 * i) * ld);
; }
; __device__ __forceinline__ void p0_convert_items(const Params& p, LAS unsigned char* lds, int it_lo, int it_hi) {
;     ...
;     float ta[32], tb[32]; int it = it_lo + gw;
;     if (it < it_hi) { p0_item_load(p, it, ta, lane);
;         for (;;) { const int it2 = it + NGW; const bool h2 = it2 < it_hi; if (h2) p0_item_load(p, it2, tb, lane);
;             p0_item_store(p, it, ta, scr, lane); if (!h2) break;
;             const int it3 = it2 + NGW; const bool h3 = it3 < it_hi; if (h3) p0_item_load(p, it3, ta, lane);
;             p0_item_store(p, it2, tb, scr, lane); if (!h3) break;
;             it = it3; } }
.LBB0_115:
	s_add_i32 s37, s24, s25
	s_add_i32 s36, s35, s24
	s_add_i32 s38, s37, 0x5800
	s_cmpk_lt_i32 s38, 0x6800
	s_cselect_b64 s[14:15], -1, 0
	s_cmpk_gt_i32 s38, 0x67ff
	s_cbranch_scc0 .Lp1c_haveA_1
	global_load_dword v255, v183, s[92:93]
	global_load_dword v255, v183, s[92:93]
	global_load_dword v255, v183, s[92:93]
	global_load_dword v255, v183, s[92:93]
	global_load_dword v255, v183, s[92:93]
	global_load_dword v255, v183, s[92:93]
	global_load_dword v255, v183, s[92:93]
	global_load_dword v255, v183, s[92:93]
	global_load_dword v255, v183, s[92:93]
	global_load_dword v255, v183, s[92:93]
	global_load_dword v255, v183, s[92:93]
	global_load_dword v255, v183, s[92:93]
	global_load_dword v255, v183, s[92:93]
	global_load_dword v255, v183, s[92:93]
	global_load_dword v255, v183, s[92:93]
	global_load_dword v255, v183, s[92:93]
	global_load_dword v255, v183, s[92:93]
	global_load_dword v255, v183, s[92:93]
	global_load_dword v255, v183, s[92:93]
	global_load_dword v255, v183, s[92:93]
	global_load_dword v255, v183, s[92:93]
	global_load_dword v255, v183, s[92:93]
	global_load_dword v255, v183, s[92:93]
	global_load_dword v255, v183, s[92:93]
	global_load_dword v255, v183, s[92:93]
	global_load_dword v255, v183, s[92:93]
	global_load_dword v255, v183, s[92:93]
	global_load_dword v255, v183, s[92:93]
	global_load_dword v255, v183, s[92:93]
	global_load_dword v255, v183, s[92:93]
	global_load_dword v255, v183, s[92:93]
	global_load_dword v255, v183, s[92:93]
	s_branch .LBB0_124
.Lp1c_haveA_1:
	s_cmpk_lt_i32 s38, 0x2000
	s_cbranch_scc1 .LBB0_120
	s_cmpk_gt_u32 s38, 0x27ff
	s_cbranch_scc0 .LBB0_121
	s_cmpk_gt_u32 s38, 0x57ff
	s_cbranch_scc1 .LBB0_180
	v_readlane_b32 s40, v253, 32
	v_readlane_b32 s48, v253, 40
	v_readlane_b32 s49, v253, 41
	s_add_i32 s20, s36, 0xffffd800
	s_mov_b64 s[0:1], 0x3000
	s_movk_i32 s21, 0x180
	v_readlane_b32 s41, v253, 33
	v_readlane_b32 s42, v253, 34
	v_readlane_b32 s43, v253, 35
	v_readlane_b32 s44, v253, 36
	v_readlane_b32 s45, v253, 37
	v_readlane_b32 s46, v253, 38
	v_readlane_b32 s47, v253, 39
	v_readlane_b32 s50, v253, 42
	v_readlane_b32 s51, v253, 43
	v_readlane_b32 s52, v253, 44
	v_readlane_b32 s53, v253, 45
	v_readlane_b32 s54, v253, 46
	v_readlane_b32 s55, v253, 47
	s_mov_b64 s[16:17], s[48:49]
	s_cbranch_execz .LBB0_122
	s_branch .LBB0_123

; #define LAS __attribute__((address_space(3)))
; __device__ __forceinline__ unsigned pk2(float lo, float hi) { return f2bf(lo) | (f2bf(hi) << 16); }
; __device__ __forceinline__ void p0_item_store(const Params& p, int it, const float (&t)[32], LAS float* scr, int lane) {
;     const float* W; int ld, nblk, K, r; bf16_t* WT; bool uz; p0_item_decode(p, it, W, ld, nblk, K, WT, uz, r);
;     const int kb = r / nblk, nb = r % nblk, k0 = 64 * kb, n0 = 32 * nb;
; #pragma unroll
;     for (int i = 0; i < 32; ++i) { const int kk = 2 * i + (lane >> 5); scr[kk * 33 + (lane & 31)] = t[i]; }
;     asm volatile("s_waitcnt lgkmcnt(0)" ::: "memory");
;     const int c = lane & 7;
; #pragma unroll
;     for (int j = 0; j < 4; ++j) { const int n = (lane >> 3) + 8 * j; const LAS float* s = scr + (8 * c) * 33 + n;
;         u32x4 o; o.x = pk2(s[0 * 33], s[1 * 33]); o.y = pk2(s[2 * 33], s[3 * 33]); o.z = pk2(s[4 * 33], s[5 * 33]); o.w = pk2(s[6 * 33], s[7 * 33]);
;         int nd = n0 + n;
;         if (uz) { const int cc = nd & (CW - 1); nd = nd < CW ? 8 * (cc >> 2) + (cc & 3) : (nd < 2 * CW ? 2 * CW + cc : 8 * (cc >> 2) + 4 + (cc & 3)); }
;         u32x4* dp = (u32x4*)(WT + (size_t)nd * K + k0 + 8 * c);
;         if (it < P0_I0) *dp = o; else __builtin_nontemporal_store(o, dp); }
;     asm volatile("s_waitcnt lgkmcnt(0)" ::: "memory");
.LBB0_132:
	v_cndmask_b32_e64 v36, 0, 1, s[20:21]
	v_cmp_ne_u32_e64 s[0:1], 1, v36
	v_cvt_f32_u32_e32 v36, s22
	s_sub_i32 s41, 0, s22
	s_abs_i32 s40, s35
	s_ashr_i32 s39, s35, 31
	v_rcp_iflag_f32_e32 v36, v36
	v_add_u32_e32 v92, 0x400, v53
	v_add_u32_e32 v86, 0x800, v53
	v_add_u32_e32 v87, 0xc00, v53
	v_mul_f32_e32 v36, 0x4f7ffffe, v36
	v_cvt_u32_f32_e32 v36, v36
	v_add_u32_e32 v88, 0x1000, v53
	v_add_u32_e32 v89, 0x1400, v53
	v_add_u32_e32 v90, 0x1800, v53
	v_readfirstlane_b32 s23, v36
	s_mul_i32 s41, s41, s23
	s_mul_hi_u32 s41, s23, s41
	s_add_i32 s23, s23, s41
	s_mul_hi_u32 s23, s40, s23
	s_mul_i32 s41, s23, s22
	s_sub_i32 s40, s40, s41
	s_add_i32 s42, s23, 1
	s_sub_i32 s41, s40, s22
	s_cmp_ge_u32 s40, s22
	s_cselect_b32 s23, s42, s23
	v_add_u32_e32 v91, 0x1c00, v53
	s_waitcnt vmcnt(62)
	ds_write2_b32 v53, v0, v1 offset1:66
	s_waitcnt vmcnt(60)
	ds_write2_b32 v53, v2, v3 offset0:132 offset1:198
	s_cselect_b32 s40, s41, s40
	s_add_i32 s41, s23, 1
	s_waitcnt vmcnt(58)
	ds_write2_b32 v92, v4, v5 offset0:8 offset1:74
	s_waitcnt vmcnt(56)
	ds_write2_b32 v92, v6, v7 offset0:140 offset1:206
	s_waitcnt vmcnt(54)
	ds_write2_b32 v86, v8, v9 offset0:16 offset1:82
	s_waitcnt vmcnt(52)
	ds_write2_b32 v86, v10, v11 offset0:148 offset1:214
	s_waitcnt vmcnt(50)
	ds_write2_b32 v87, v12, v13 offset0:24 offset1:90
	s_waitcnt vmcnt(48)
	ds_write2_b32 v87, v14, v15 offset0:156 offset1:222
	s_waitcnt vmcnt(46)
	ds_write2_b32 v88, v16, v17 offset0:32 offset1:98
	s_waitcnt vmcnt(44)
	ds_write2_b32 v88, v18, v19 offset0:164 offset1:230
	s_waitcnt vmcnt(42)
	ds_write2_b32 v89, v20, v21 offset0:40 offset1:106
	s_waitcnt vmcnt(40)
	ds_write2_b32 v89, v22, v23 offset0:172 offset1:238
	s_waitcnt vmcnt(38)
	ds_write2_b32 v90, v24, v25 offset0:48 offset1:114
	s_waitcnt vmcnt(36)
	ds_write2_b32 v90, v26, v27 offset0:180 offset1:246
	s_waitcnt vmcnt(34)
	ds_write2_b32 v91, v28, v29 offset0:56 offset1:122
	s_waitcnt vmcnt(32)
	ds_write2_b32 v91, v30, v31 offset0:188 offset1:254
	s_cmp_ge_u32 s40, s22
	s_waitcnt lgkmcnt(0)
	s_cselect_b32 s23, s41, s23
	ds_read2_b32 v[44:45], v48 offset1:33
	ds_read2_b32 v[42:43], v48 offset0:66 offset1:99
	ds_read2_b32 v[40:41], v48 offset0:132 offset1:165
	ds_read2_b32 v[38:39], v48 offset0:198 offset1:231
	s_xor_b32 s23, s23, s39
	s_sub_i32 s39, s23, s39
	s_mul_i32 s22, s39, s22
	s_sub_i32 s22, s35, s22
	s_lshl_b32 s35, s22, 5
	s_andn2_b64 vcc, exec, s[20:21]
	v_or_b32_e32 v93, s35, v46
	s_cbranch_vccnz .LBB0_142
	v_and_b32_e32 v36, 0xfe7, v93
	v_cmp_lt_i32_e32 vcc, s27, v93
	s_and_saveexec_b64 s[20:21], vcc
	s_xor_b64 s[20:21], exec, s[20:21]
	s_cbranch_execz .LBB0_139
	s_cmpk_gt_u32 s35, 0x1fff
	s_mov_b64 s[22:23], -1
	s_cbranch_scc0 .LBB0_136
	v_lshlrev_b32_e32 v37, 1, v36
	v_and_or_b32 v93, v37, s28, v52
	s_mov_b64 s[22:23], 0

; #define LAS __attribute__((address_space(3)))
; __device__ __forceinline__ unsigned pk2(float lo, float hi) { return f2bf(lo) | (f2bf(hi) << 16); }
; __device__ __forceinline__ void p0_item_store(const Params& p, int it, const float (&t)[32], LAS float* scr, int lane) {
;     ...
;     for (int j = 0; j < 4; ++j) { const int n = (lane >> 3) + 8 * j; const LAS float* s = scr + (8 * c) * 33 + n;
;         u32x4 o; o.x = pk2(s[0 * 33], s[1 * 33]); o.y = pk2(s[2 * 33], s[3 * 33]); o.z = pk2(s[4 * 33], s[5 * 33]); o.w = pk2(s[6 * 33], s[7 * 33]);
;         int nd = n0 + n;
;         if (uz) { const int cc = nd & (CW - 1); nd = nd < CW ? 8 * (cc >> 2) + (cc & 3) : (nd < 2 * CW ? 2 * CW + cc : 8 * (cc >> 2) + 4 + (cc & 3)); }
;         u32x4* dp = (u32x4*)(WT + (size_t)nd * K + k0 + 8 * c);
;         if (it < P0_I0) *dp = o; else __builtin_nontemporal_store(o, dp); }
; __device__ __forceinline__ void p0_convert_items(const Params& p, LAS unsigned char* lds, int it_lo, int it_hi) {
;     ...
;     float ta[32], tb[32]; int it = it_lo + gw;
;     if (it < it_hi) { p0_item_load(p, it, ta, lane);
;         for (;;) { const int it2 = it + NGW; const bool h2 = it2 < it_hi; if (h2) p0_item_load(p, it2, tb, lane);
;             p0_item_store(p, it, ta, scr, lane); if (!h2) break;
;             const int it3 = it2 + NGW; const bool h3 = it3 < it_hi; if (h3) p0_item_load(p, it3, ta, lane);
;             p0_item_store(p, it2, tb, scr, lane); if (!h3) break;
;             it = it3; } }
.LBB0_172:
	s_waitcnt lgkmcnt(3)
	v_bfe_u32 v94, v45, 16, 1
	v_add3_u32 v45, v45, v94, s29
	v_bfe_u32 v94, v44, 16, 1
	v_add3_u32 v44, v44, v94, s29
	v_lshrrev_b32_e32 v44, 16, v44
	v_and_or_b32 v94, v45, s30, v44
	s_waitcnt lgkmcnt(2)
	v_bfe_u32 v44, v43, 16, 1
	v_add3_u32 v43, v43, v44, s29
	v_bfe_u32 v44, v42, 16, 1
	v_add3_u32 v42, v42, v44, s29
	v_lshrrev_b32_e32 v42, 16, v42
	v_and_or_b32 v95, v43, s30, v42
	s_waitcnt lgkmcnt(1)
	v_bfe_u32 v42, v41, 16, 1
	v_add3_u32 v41, v41, v42, s29
	v_bfe_u32 v42, v40, 16, 1
	v_add3_u32 v40, v40, v42, s29
	v_lshrrev_b32_e32 v40, 16, v40
	v_and_or_b32 v96, v41, s30, v40
	s_waitcnt lgkmcnt(0)
	v_bfe_u32 v40, v39, 16, 1
	v_add3_u32 v39, v39, v40, s29
	v_bfe_u32 v40, v38, 16, 1
	v_add3_u32 v38, v38, v40, s29
	v_lshrrev_b32_e32 v38, 16, v38
	v_and_or_b32 v97, v39, s30, v38
	v_ashrrev_i32_e32 v38, 31, v93
	v_mul_lo_u32 v40, s17, v93
	v_mul_lo_u32 v41, s16, v38
	v_mad_u64_u32 v[38:39], s[0:1], s16, v93, 0
	v_add3_u32 v39, v39, v41, v40
	v_lshl_add_u64 v[36:37], v[38:39], 1, v[36:37]
	global_store_dwordx4 v[36:37], v[94:97], off
	s_waitcnt lgkmcnt(0)
	s_andn2_b64 vcc, exec, s[14:15]
	s_mov_b64 s[14:15], -1
	s_cbranch_vccnz .LBB0_114
	s_add_i32 s25, s26, s25
	s_add_i32 s35, s36, s24
	s_add_i32 s0, s25, 0x5800
	s_cmpk_gt_i32 s0, 0x67ff
	s_cselect_b64 s[14:15], -1, 0
	s_and_b64 vcc, exec, s[14:15]
	s_cbranch_vccz .Lp1c_haveB_1
	global_load_dword v255, v183, s[92:93]
	global_load_dword v255, v183, s[92:93]
	global_load_dword v255, v183, s[92:93]
	global_load_dword v255, v183, s[92:93]
	global_load_dword v255, v183, s[92:93]
	global_load_dword v255, v183, s[92:93]
	global_load_dword v255, v183, s[92:93]
	global_load_dword v255, v183, s[92:93]
	global_load_dword v255, v183, s[92:93]
	global_load_dword v255, v183, s[92:93]
	global_load_dword v255, v183, s[92:93]
	global_load_dword v255, v183, s[92:93]
	global_load_dword v255, v183, s[92:93]
	global_load_dword v255, v183, s[92:93]
	global_load_dword v255, v183, s[92:93]
	global_load_dword v255, v183, s[92:93]
	global_load_dword v255, v183, s[92:93]
	global_load_dword v255, v183, s[92:93]
	global_load_dword v255, v183, s[92:93]
	global_load_dword v255, v183, s[92:93]
	global_load_dword v255, v183, s[92:93]
	global_load_dword v255, v183, s[92:93]
	global_load_dword v255, v183, s[92:93]
	global_load_dword v255, v183, s[92:93]
	global_load_dword v255, v183, s[92:93]
	global_load_dword v255, v183, s[92:93]
	global_load_dword v255, v183, s[92:93]
	global_load_dword v255, v183, s[92:93]
	global_load_dword v255, v183, s[92:93]
	global_load_dword v255, v183, s[92:93]
	global_load_dword v255, v183, s[92:93]
	global_load_dword v255, v183, s[92:93]
	s_branch .LBB0_184
.Lp1c_haveB_1:
	s_cmpk_lt_i32 s0, 0x2000
	s_cbranch_scc1 .LBB0_179
	s_cmpk_gt_u32 s0, 0x27ff
	s_cbranch_scc0 .LBB0_181
	s_cmpk_gt_u32 s0, 0x57ff
	s_cbranch_scc1 .LBB0_232
	v_readlane_b32 s40, v253, 32
	v_readlane_b32 s48, v253, 40
	v_readlane_b32 s49, v253, 41
	s_add_i32 s20, s35, 0xffffd800
	s_mov_b64 s[0:1], 0x3000
	s_movk_i32 s21, 0x180
	v_readlane_b32 s41, v253, 33
	v_readlane_b32 s42, v253, 34
	v_readlane_b32 s43, v253, 35
	v_readlane_b32 s44, v253, 36
	v_readlane_b32 s45, v253, 37
	v_readlane_b32 s46, v253, 38
	v_readlane_b32 s47, v253, 39
	v_readlane_b32 s50, v253, 42
	v_readlane_b32 s51, v253, 43
	v_readlane_b32 s52, v253, 44
	v_readlane_b32 s53, v253, 45
	v_readlane_b32 s54, v253, 46
	v_readlane_b32 s55, v253, 47
	s_mov_b64 s[16:17], s[48:49]
	s_cbranch_execz .LBB0_182
	s_branch .LBB0_183

; #define LAS __attribute__((address_space(3)))
; __device__ __forceinline__ void p0_item_store(const Params& p, int it, const float (&t)[32], LAS float* scr, int lane) {
;     const float* W; int ld, nblk, K, r; bf16_t* WT; bool uz; p0_item_decode(p, it, W, ld, nblk, K, WT, uz, r);
;     const int kb = r / nblk, nb = r % nblk, k0 = 64 * kb, n0 = 32 * nb;
; #pragma unroll
;     for (int i = 0; i < 32; ++i) { const int kk = 2 * i + (lane >> 5); scr[kk * 33 + (lane & 31)] = t[i]; }
;     asm volatile("s_waitcnt lgkmcnt(0)" ::: "memory");
;     const int c = lane & 7;
; #pragma unroll
;     for (int j = 0; j < 4; ++j) { const int n = (lane >> 3) + 8 * j; const LAS float* s = scr + (8 * c) * 33 + n;
.LBB0_192:
	s_waitcnt vmcnt(32)
	v_cvt_f32_u32_e32 v36, s22
	s_sub_i32 s23, 0, s22
	s_abs_i32 s1, s36
	s_ashr_i32 s0, s36, 31
	v_rcp_iflag_f32_e32 v36, v36
	ds_write2_b32 v53, v61, v60 offset1:66
	ds_write2_b32 v53, v59, v58 offset0:132 offset1:198
	ds_write2_b32 v92, v57, v56 offset0:8 offset1:74
	ds_write2_b32 v92, v55, v54 offset0:140 offset1:206
	ds_write2_b32 v86, v62, v63 offset0:16 offset1:82
	ds_write2_b32 v86, v64, v65 offset0:148 offset1:214
	ds_write2_b32 v87, v66, v67 offset0:24 offset1:90
	ds_write2_b32 v87, v68, v69 offset0:156 offset1:222
	ds_write2_b32 v88, v70, v71 offset0:32 offset1:98
	ds_write2_b32 v88, v72, v73 offset0:164 offset1:230
	ds_write2_b32 v89, v74, v75 offset0:40 offset1:106
	ds_write2_b32 v89, v76, v77 offset0:172 offset1:238
	ds_write2_b32 v90, v78, v79 offset0:48 offset1:114
	ds_write2_b32 v90, v80, v81 offset0:180 offset1:246
	ds_write2_b32 v91, v82, v83 offset0:56 offset1:122
	ds_write2_b32 v91, v84, v85 offset0:188 offset1:254
	v_mul_f32_e32 v36, 0x4f7ffffe, v36
	v_cvt_u32_f32_e32 v36, v36
	s_waitcnt lgkmcnt(0)
	ds_read2_b32 v[44:45], v48 offset1:33
	ds_read2_b32 v[42:43], v48 offset0:66 offset1:99
	ds_read2_b32 v[40:41], v48 offset0:132 offset1:165
	ds_read2_b32 v[38:39], v48 offset0:198 offset1:231
	v_readfirstlane_b32 s37, v36
	s_mul_i32 s23, s23, s37
	s_mul_hi_u32 s23, s37, s23
	s_add_i32 s37, s37, s23
	s_mul_hi_u32 s23, s1, s37
	s_mul_i32 s37, s23, s22
	s_sub_i32 s1, s1, s37
	s_add_i32 s38, s23, 1
	s_sub_i32 s37, s1, s22
	s_cmp_ge_u32 s1, s22
	s_cselect_b32 s23, s38, s23
	s_cselect_b32 s1, s37, s1
	s_add_i32 s37, s23, 1
	s_cmp_ge_u32 s1, s22
	s_cselect_b32 s1, s37, s23
	s_xor_b32 s1, s1, s0
	s_sub_i32 s37, s1, s0
	s_mul_i32 s0, s37, s22
	s_sub_i32 s0, s36, s0
	s_lshl_b32 s36, s0, 5
	v_cndmask_b32_e64 v36, 0, 1, s[20:21]
	v_cmp_ne_u32_e64 s[0:1], 1, v36
	s_andn2_b64 vcc, exec, s[20:21]
	v_or_b32_e32 v86, s36, v46
	s_cbranch_vccnz .LBB0_202
	v_and_b32_e32 v36, 0xfe7, v86
	v_cmp_lt_i32_e32 vcc, s27, v86
	s_and_saveexec_b64 s[20:21], vcc
	s_xor_b64 s[20:21], exec, s[20:21]
	s_cbranch_execz .LBB0_199
	s_cmpk_gt_u32 s36, 0x1fff
	s_mov_b64 s[22:23], -1
	s_cbranch_scc0 .LBB0_196
	v_lshlrev_b32_e32 v37, 1, v36
	v_and_or_b32 v86, v37, s28, v52
	s_mov_b64 s[22:23], 0

; __device__ __forceinline__ void p0_item_decode(const Params& p, int it, const float*& W, int& ld, int& nblk, int& K, bf16_t*& WT, bool& uzmap, int& r) {
;     r = it; uzmap = false;
;     if (r < P0_I0) { W = p.w_in0; ld = LDW0; nblk = N1 / 32; K = DM; WT = (bf16_t*)(p.ws + WS_W0T); return; } r -= P0_I0;
;     if (r < P0_I1) { W = p.w_out0; ld = DM; nblk = DM / 32; K = DM; WT = (bf16_t*)(p.ws + WS_WO0T); return; } r -= P0_I1;
;     if (r < P0_I2) { W = p.w_in1; ld = N3; nblk = N3 / 32; K = DM; WT = (bf16_t*)(p.ws + WS_W1T); uzmap = true; return; } r -= P0_I2;
;     W = p.w_out1; ld = DM; nblk = DM / 32; K = CW; WT = (bf16_t*)(p.ws + WS_WO1T);
; }
; __device__ __forceinline__ void p0_item_load(const Params& p, int it, float (&t)[32], int lane) {
;     const float* W; int ld, nblk, K, r; bf16_t* WT; bool uz; p0_item_decode(p, it, W, ld, nblk, K, WT, uz, r);
;     const int kb = r / nblk, nb = r % nblk, k0 = 64 * kb, n0 = 32 * nb;
;     const float* src = W + (size_t)(k0 + (lane >> 5)) * ld + n0 + (lane & 31);
; #pragma unroll
;     for (int i = 0; i < 32; ++i) t[i] = __builtin_nontemporal_load(src + (size_t)(2 * i) * ld);
; }
; __device__ __forceinline__ void p0_convert_items(const Params& p, LAS unsigned char* lds, int it_lo, int it_hi) {
;     ...
;     float ta[32], tb[32]; int it = it_lo + gw;
;     if (it < it_hi) { p0_item_load(p, it, ta, lane);
;         for (;;) { const int it2 = it + NGW; const bool h2 = it2 < it_hi; if (h2) p0_item_load(p, it2, tb, lane);
;             p0_item_store(p, it, ta, scr, lane); if (!h2) break;
;             const int it3 = it2 + NGW; const bool h3 = it3 < it_hi; if (h3) p0_item_load(p, it3, ta, lane);
;             p0_item_store(p, it2, tb, scr, lane); if (!h3) break;
;             it = it3; } }
.LBB0_391:
	s_add_i32 s35, s22, s23
	s_add_i32 s34, s33, s22
	s_add_i32 s36, s35, 0x5800
	s_cmpk_lt_i32 s36, 0x6800
	s_cselect_b64 s[12:13], -1, 0
	s_cmpk_gt_i32 s36, 0x67ff
	s_cbranch_scc0 .Lp1c_haveA_2
	global_load_dword v255, v183, s[92:93]
	global_load_dword v255, v183, s[92:93]
	global_load_dword v255, v183, s[92:93]
	global_load_dword v255, v183, s[92:93]
	global_load_dword v255, v183, s[92:93]
	global_load_dword v255, v183, s[92:93]
	global_load_dword v255, v183, s[92:93]
	global_load_dword v255, v183, s[92:93]
	global_load_dword v255, v183, s[92:93]
	global_load_dword v255, v183, s[92:93]
	global_load_dword v255, v183, s[92:93]
	global_load_dword v255, v183, s[92:93]
	global_load_dword v255, v183, s[92:93]
	global_load_dword v255, v183, s[92:93]
	global_load_dword v255, v183, s[92:93]
	global_load_dword v255, v183, s[92:93]
	global_load_dword v255, v183, s[92:93]
	global_load_dword v255, v183, s[92:93]
	global_load_dword v255, v183, s[92:93]
	global_load_dword v255, v183, s[92:93]
	global_load_dword v255, v183, s[92:93]
	global_load_dword v255, v183, s[92:93]
	global_load_dword v255, v183, s[92:93]
	global_load_dword v255, v183, s[92:93]
	global_load_dword v255, v183, s[92:93]
	global_load_dword v255, v183, s[92:93]
	global_load_dword v255, v183, s[92:93]
	global_load_dword v255, v183, s[92:93]
	global_load_dword v255, v183, s[92:93]
	global_load_dword v255, v183, s[92:93]
	global_load_dword v255, v183, s[92:93]
	global_load_dword v255, v183, s[92:93]
	s_branch .LBB0_400
.Lp1c_haveA_2:
	s_cmpk_lt_i32 s36, 0x2000
	s_cbranch_scc1 .LBB0_396
	s_cmpk_gt_u32 s36, 0x27ff
	s_cbranch_scc0 .LBB0_397
	s_cmpk_gt_u32 s36, 0x57ff
	s_cbranch_scc1 .LBB0_456
	v_readlane_b32 s40, v253, 32
	v_readlane_b32 s48, v253, 40
	v_readlane_b32 s49, v253, 41
	s_add_i32 s18, s34, 0xffffd800
	s_mov_b64 s[0:1], 0x3000
	s_movk_i32 s19, 0x180
	v_readlane_b32 s41, v253, 33
	v_readlane_b32 s42, v253, 34
	v_readlane_b32 s43, v253, 35
	v_readlane_b32 s44, v253, 36
	v_readlane_b32 s45, v253, 37
	v_readlane_b32 s46, v253, 38
	v_readlane_b32 s47, v253, 39
	v_readlane_b32 s50, v253, 42
	v_readlane_b32 s51, v253, 43
	v_readlane_b32 s52, v253, 44
	v_readlane_b32 s53, v253, 45
	v_readlane_b32 s54, v253, 46
	v_readlane_b32 s55, v253, 47
	s_mov_b64 s[14:15], s[48:49]
	s_cbranch_execz .LBB0_398
	s_branch .LBB0_399

; #define LAS __attribute__((address_space(3)))
; __device__ __forceinline__ unsigned pk2(float lo, float hi) { return f2bf(lo) | (f2bf(hi) << 16); }
; __device__ __forceinline__ void p0_item_store(const Params& p, int it, const float (&t)[32], LAS float* scr, int lane) {
;     const float* W; int ld, nblk, K, r; bf16_t* WT; bool uz; p0_item_decode(p, it, W, ld, nblk, K, WT, uz, r);
;     const int kb = r / nblk, nb = r % nblk, k0 = 64 * kb, n0 = 32 * nb;
; #pragma unroll
;     for (int i = 0; i < 32; ++i) { const int kk = 2 * i + (lane >> 5); scr[kk * 33 + (lane & 31)] = t[i]; }
;     asm volatile("s_waitcnt lgkmcnt(0)" ::: "memory");
;     const int c = lane & 7;
; #pragma unroll
;     for (int j = 0; j < 4; ++j) { const int n = (lane >> 3) + 8 * j; const LAS float* s = scr + (8 * c) * 33 + n;
;         u32x4 o; o.x = pk2(s[0 * 33], s[1 * 33]); o.y = pk2(s[2 * 33], s[3 * 33]); o.z = pk2(s[4 * 33], s[5 * 33]); o.w = pk2(s[6 * 33], s[7 * 33]);
;         int nd = n0 + n;
;         if (uz) { const int cc = nd & (CW - 1); nd = nd < CW ? 8 * (cc >> 2) + (cc & 3) : (nd < 2 * CW ? 2 * CW + cc : 8 * (cc >> 2) + 4 + (cc & 3)); }
;         u32x4* dp = (u32x4*)(WT + (size_t)nd * K + k0 + 8 * c);
;         if (it < P0_I0) *dp = o; else __builtin_nontemporal_store(o, dp); }
;     asm volatile("s_waitcnt lgkmcnt(0)" ::: "memory");
.LBB0_408:
	v_cndmask_b32_e64 v36, 0, 1, s[18:19]
	v_cmp_ne_u32_e64 s[0:1], 1, v36
	v_cvt_f32_u32_e32 v36, s20
	s_sub_i32 s39, 0, s20
	s_abs_i32 s38, s33
	s_ashr_i32 s37, s33, 31
	v_rcp_iflag_f32_e32 v36, v36
	v_add_u32_e32 v92, 0x400, v53
	v_add_u32_e32 v86, 0x800, v53
	v_add_u32_e32 v87, 0xc00, v53
	v_mul_f32_e32 v36, 0x4f7ffffe, v36
	v_cvt_u32_f32_e32 v36, v36
	v_add_u32_e32 v88, 0x1000, v53
	v_add_u32_e32 v89, 0x1400, v53
	v_add_u32_e32 v90, 0x1800, v53
	v_readfirstlane_b32 s21, v36
	s_mul_i32 s39, s39, s21
	s_mul_hi_u32 s39, s21, s39
	s_add_i32 s21, s21, s39
	s_mul_hi_u32 s21, s38, s21
	s_mul_i32 s39, s21, s20
	s_sub_i32 s38, s38, s39
	s_add_i32 s40, s21, 1
	s_sub_i32 s39, s38, s20
	s_cmp_ge_u32 s38, s20
	s_cselect_b32 s21, s40, s21
	v_add_u32_e32 v91, 0x1c00, v53
	s_waitcnt vmcnt(62)
	ds_write2_b32 v53, v0, v1 offset1:66
	s_waitcnt vmcnt(60)
	ds_write2_b32 v53, v2, v3 offset0:132 offset1:198
	s_cselect_b32 s38, s39, s38
	s_add_i32 s39, s21, 1
	s_waitcnt vmcnt(58)
	ds_write2_b32 v92, v4, v5 offset0:8 offset1:74
	s_waitcnt vmcnt(56)
	ds_write2_b32 v92, v6, v7 offset0:140 offset1:206
	s_waitcnt vmcnt(54)
	ds_write2_b32 v86, v8, v9 offset0:16 offset1:82
	s_waitcnt vmcnt(52)
	ds_write2_b32 v86, v10, v11 offset0:148 offset1:214
	s_waitcnt vmcnt(50)
	ds_write2_b32 v87, v12, v13 offset0:24 offset1:90
	s_waitcnt vmcnt(48)
	ds_write2_b32 v87, v14, v15 offset0:156 offset1:222
	s_waitcnt vmcnt(46)
	ds_write2_b32 v88, v16, v17 offset0:32 offset1:98
	s_waitcnt vmcnt(44)
	ds_write2_b32 v88, v18, v19 offset0:164 offset1:230
	s_waitcnt vmcnt(42)
	ds_write2_b32 v89, v20, v21 offset0:40 offset1:106
	s_waitcnt vmcnt(40)
	ds_write2_b32 v89, v22, v23 offset0:172 offset1:238
	s_waitcnt vmcnt(38)
	ds_write2_b32 v90, v24, v25 offset0:48 offset1:114
	s_waitcnt vmcnt(36)
	ds_write2_b32 v90, v26, v27 offset0:180 offset1:246
	s_waitcnt vmcnt(34)
	ds_write2_b32 v91, v28, v29 offset0:56 offset1:122
	s_waitcnt vmcnt(32)
	ds_write2_b32 v91, v30, v31 offset0:188 offset1:254
	s_cmp_ge_u32 s38, s20
	s_waitcnt lgkmcnt(0)
	s_cselect_b32 s21, s39, s21
	ds_read2_b32 v[44:45], v48 offset1:33
	ds_read2_b32 v[42:43], v48 offset0:66 offset1:99
	ds_read2_b32 v[40:41], v48 offset0:132 offset1:165
	ds_read2_b32 v[38:39], v48 offset0:198 offset1:231
	s_xor_b32 s21, s21, s37
	s_sub_i32 s37, s21, s37
	s_mul_i32 s20, s37, s20
	s_sub_i32 s20, s33, s20
	s_lshl_b32 s33, s20, 5
	s_andn2_b64 vcc, exec, s[18:19]
	v_or_b32_e32 v93, s33, v46
	s_cbranch_vccnz .LBB0_418
	v_and_b32_e32 v36, 0xfe7, v93
	v_cmp_lt_i32_e32 vcc, s25, v93
	s_and_saveexec_b64 s[18:19], vcc
	s_xor_b64 s[18:19], exec, s[18:19]
	s_cbranch_execz .LBB0_415
	s_cmpk_gt_u32 s33, 0x1fff
	s_mov_b64 s[20:21], -1
	s_cbranch_scc0 .LBB0_412
	v_lshlrev_b32_e32 v37, 1, v36
	v_and_or_b32 v93, v37, s26, v52
	s_mov_b64 s[20:21], 0

; #define LAS __attribute__((address_space(3)))
; __device__ __forceinline__ unsigned pk2(float lo, float hi) { return f2bf(lo) | (f2bf(hi) << 16); }
; __device__ __forceinline__ void p0_item_store(const Params& p, int it, const float (&t)[32], LAS float* scr, int lane) {
;     ...
;     for (int j = 0; j < 4; ++j) { const int n = (lane >> 3) + 8 * j; const LAS float* s = scr + (8 * c) * 33 + n;
;         u32x4 o; o.x = pk2(s[0 * 33], s[1 * 33]); o.y = pk2(s[2 * 33], s[3 * 33]); o.z = pk2(s[4 * 33], s[5 * 33]); o.w = pk2(s[6 * 33], s[7 * 33]);
;         int nd = n0 + n;
;         if (uz) { const int cc = nd & (CW - 1); nd = nd < CW ? 8 * (cc >> 2) + (cc & 3) : (nd < 2 * CW ? 2 * CW + cc : 8 * (cc >> 2) + 4 + (cc & 3)); }
;         u32x4* dp = (u32x4*)(WT + (size_t)nd * K + k0 + 8 * c);
;         if (it < P0_I0) *dp = o; else __builtin_nontemporal_store(o, dp); }
; __device__ __forceinline__ void p0_convert_items(const Params& p, LAS unsigned char* lds, int it_lo, int it_hi) {
;     ...
;     float ta[32], tb[32]; int it = it_lo + gw;
;     if (it < it_hi) { p0_item_load(p, it, ta, lane);
;         for (;;) { const int it2 = it + NGW; const bool h2 = it2 < it_hi; if (h2) p0_item_load(p, it2, tb, lane);
;             p0_item_store(p, it, ta, scr, lane); if (!h2) break;
;             const int it3 = it2 + NGW; const bool h3 = it3 < it_hi; if (h3) p0_item_load(p, it3, ta, lane);
;             p0_item_store(p, it2, tb, scr, lane); if (!h3) break;
;             it = it3; } }
.LBB0_448:
	s_waitcnt lgkmcnt(3)
	v_bfe_u32 v94, v45, 16, 1
	v_add3_u32 v45, v45, v94, s27
	v_bfe_u32 v94, v44, 16, 1
	v_add3_u32 v44, v44, v94, s27
	v_lshrrev_b32_e32 v44, 16, v44
	v_and_or_b32 v94, v45, s28, v44
	s_waitcnt lgkmcnt(2)
	v_bfe_u32 v44, v43, 16, 1
	v_add3_u32 v43, v43, v44, s27
	v_bfe_u32 v44, v42, 16, 1
	v_add3_u32 v42, v42, v44, s27
	v_lshrrev_b32_e32 v42, 16, v42
	v_and_or_b32 v95, v43, s28, v42
	s_waitcnt lgkmcnt(1)
	v_bfe_u32 v42, v41, 16, 1
	v_add3_u32 v41, v41, v42, s27
	v_bfe_u32 v42, v40, 16, 1
	v_add3_u32 v40, v40, v42, s27
	v_lshrrev_b32_e32 v40, 16, v40
	v_and_or_b32 v96, v41, s28, v40
	s_waitcnt lgkmcnt(0)
	v_bfe_u32 v40, v39, 16, 1
	v_add3_u32 v39, v39, v40, s27
	v_bfe_u32 v40, v38, 16, 1
	v_add3_u32 v38, v38, v40, s27
	v_lshrrev_b32_e32 v38, 16, v38
	v_and_or_b32 v97, v39, s28, v38
	v_ashrrev_i32_e32 v38, 31, v93
	v_mul_lo_u32 v40, s15, v93
	v_mul_lo_u32 v41, s14, v38
	v_mad_u64_u32 v[38:39], s[0:1], s14, v93, 0
	v_add3_u32 v39, v39, v41, v40
	v_lshl_add_u64 v[36:37], v[38:39], 1, v[36:37]
	global_store_dwordx4 v[36:37], v[94:97], off
	s_waitcnt lgkmcnt(0)
	s_andn2_b64 vcc, exec, s[12:13]
	s_mov_b64 s[12:13], -1
	s_cbranch_vccnz .LBB0_390
	s_add_i32 s23, s24, s23
	s_add_i32 s33, s34, s22
	s_add_i32 s0, s23, 0x5800
	s_cmpk_gt_i32 s0, 0x67ff
	s_cselect_b64 s[12:13], -1, 0
	s_and_b64 vcc, exec, s[12:13]
	s_cbranch_vccz .Lp1c_haveB_2
	global_load_dword v255, v183, s[92:93]
	global_load_dword v255, v183, s[92:93]
	global_load_dword v255, v183, s[92:93]
	global_load_dword v255, v183, s[92:93]
	global_load_dword v255, v183, s[92:93]
	global_load_dword v255, v183, s[92:93]
	global_load_dword v255, v183, s[92:93]
	global_load_dword v255, v183, s[92:93]
	global_load_dword v255, v183, s[92:93]
	global_load_dword v255, v183, s[92:93]
	global_load_dword v255, v183, s[92:93]
	global_load_dword v255, v183, s[92:93]
	global_load_dword v255, v183, s[92:93]
	global_load_dword v255, v183, s[92:93]
	global_load_dword v255, v183, s[92:93]
	global_load_dword v255, v183, s[92:93]
	global_load_dword v255, v183, s[92:93]
	global_load_dword v255, v183, s[92:93]
	global_load_dword v255, v183, s[92:93]
	global_load_dword v255, v183, s[92:93]
	global_load_dword v255, v183, s[92:93]
	global_load_dword v255, v183, s[92:93]
	global_load_dword v255, v183, s[92:93]
	global_load_dword v255, v183, s[92:93]
	global_load_dword v255, v183, s[92:93]
	global_load_dword v255, v183, s[92:93]
	global_load_dword v255, v183, s[92:93]
	global_load_dword v255, v183, s[92:93]
	global_load_dword v255, v183, s[92:93]
	global_load_dword v255, v183, s[92:93]
	global_load_dword v255, v183, s[92:93]
	global_load_dword v255, v183, s[92:93]
	s_branch .LBB0_460
.Lp1c_haveB_2:
	s_cmpk_lt_i32 s0, 0x2000
	s_cbranch_scc1 .LBB0_455
	s_cmpk_gt_u32 s0, 0x27ff
	s_cbranch_scc0 .LBB0_457
	s_cmpk_gt_u32 s0, 0x57ff
	s_cbranch_scc1 .LBB0_508
	v_readlane_b32 s40, v253, 32
	v_readlane_b32 s48, v253, 40
	v_readlane_b32 s49, v253, 41
	s_add_i32 s18, s33, 0xffffd800
	s_mov_b64 s[0:1], 0x3000
	s_movk_i32 s19, 0x180
	v_readlane_b32 s41, v253, 33
	v_readlane_b32 s42, v253, 34
	v_readlane_b32 s43, v253, 35
	v_readlane_b32 s44, v253, 36
	v_readlane_b32 s45, v253, 37
	v_readlane_b32 s46, v253, 38
	v_readlane_b32 s47, v253, 39
	v_readlane_b32 s50, v253, 42
	v_readlane_b32 s51, v253, 43
	v_readlane_b32 s52, v253, 44
	v_readlane_b32 s53, v253, 45
	v_readlane_b32 s54, v253, 46
	v_readlane_b32 s55, v253, 47
	s_mov_b64 s[14:15], s[48:49]
	s_cbranch_execz .LBB0_458
	s_branch .LBB0_459

; #define LAS __attribute__((address_space(3)))
; __device__ __forceinline__ void p0_item_store(const Params& p, int it, const float (&t)[32], LAS float* scr, int lane) {
;     const float* W; int ld, nblk, K, r; bf16_t* WT; bool uz; p0_item_decode(p, it, W, ld, nblk, K, WT, uz, r);
;     const int kb = r / nblk, nb = r % nblk, k0 = 64 * kb, n0 = 32 * nb;
; #pragma unroll
;     for (int i = 0; i < 32; ++i) { const int kk = 2 * i + (lane >> 5); scr[kk * 33 + (lane & 31)] = t[i]; }
;     asm volatile("s_waitcnt lgkmcnt(0)" ::: "memory");
;     const int c = lane & 7;
; #pragma unroll
;     for (int j = 0; j < 4; ++j) { const int n = (lane >> 3) + 8 * j; const LAS float* s = scr + (8 * c) * 33 + n;
.LBB0_468:
	s_waitcnt vmcnt(32)
	v_cvt_f32_u32_e32 v36, s20
	s_sub_i32 s21, 0, s20
	s_abs_i32 s1, s34
	s_ashr_i32 s0, s34, 31
	v_rcp_iflag_f32_e32 v36, v36
	ds_write2_b32 v53, v61, v60 offset1:66
	ds_write2_b32 v53, v59, v58 offset0:132 offset1:198
	ds_write2_b32 v92, v57, v56 offset0:8 offset1:74
	ds_write2_b32 v92, v55, v54 offset0:140 offset1:206
	ds_write2_b32 v86, v62, v63 offset0:16 offset1:82
	ds_write2_b32 v86, v64, v65 offset0:148 offset1:214
	ds_write2_b32 v87, v66, v67 offset0:24 offset1:90
	ds_write2_b32 v87, v68, v69 offset0:156 offset1:222
	ds_write2_b32 v88, v70, v71 offset0:32 offset1:98
	ds_write2_b32 v88, v72, v73 offset0:164 offset1:230
	ds_write2_b32 v89, v74, v75 offset0:40 offset1:106
	ds_write2_b32 v89, v76, v77 offset0:172 offset1:238
	ds_write2_b32 v90, v78, v79 offset0:48 offset1:114
	ds_write2_b32 v90, v80, v81 offset0:180 offset1:246
	ds_write2_b32 v91, v82, v83 offset0:56 offset1:122
	ds_write2_b32 v91, v84, v85 offset0:188 offset1:254
	v_mul_f32_e32 v36, 0x4f7ffffe, v36
	v_cvt_u32_f32_e32 v36, v36
	s_waitcnt lgkmcnt(0)
	ds_read2_b32 v[44:45], v48 offset1:33
	ds_read2_b32 v[42:43], v48 offset0:66 offset1:99
	ds_read2_b32 v[40:41], v48 offset0:132 offset1:165
	ds_read2_b32 v[38:39], v48 offset0:198 offset1:231
	v_readfirstlane_b32 s35, v36
	s_mul_i32 s21, s21, s35
	s_mul_hi_u32 s21, s35, s21
	s_add_i32 s35, s35, s21
	s_mul_hi_u32 s21, s1, s35
	s_mul_i32 s35, s21, s20
	s_sub_i32 s1, s1, s35
	s_add_i32 s36, s21, 1
	s_sub_i32 s35, s1, s20
	s_cmp_ge_u32 s1, s20
	s_cselect_b32 s21, s36, s21
	s_cselect_b32 s1, s35, s1
	s_add_i32 s35, s21, 1
	s_cmp_ge_u32 s1, s20
	s_cselect_b32 s1, s35, s21
	s_xor_b32 s1, s1, s0
	s_sub_i32 s35, s1, s0
	s_mul_i32 s0, s35, s20
	s_sub_i32 s0, s34, s0
	s_lshl_b32 s34, s0, 5
	v_cndmask_b32_e64 v36, 0, 1, s[18:19]
	v_cmp_ne_u32_e64 s[0:1], 1, v36
	s_andn2_b64 vcc, exec, s[18:19]
	v_or_b32_e32 v86, s34, v46
	s_cbranch_vccnz .LBB0_478
	v_and_b32_e32 v36, 0xfe7, v86
	v_cmp_lt_i32_e32 vcc, s25, v86
	s_and_saveexec_b64 s[18:19], vcc
	s_xor_b64 s[18:19], exec, s[18:19]
	s_cbranch_execz .LBB0_475
	s_cmpk_gt_u32 s34, 0x1fff
	s_mov_b64 s[20:21], -1
	s_cbranch_scc0 .LBB0_472
	v_lshlrev_b32_e32 v37, 1, v36
	v_and_or_b32 v86, v37, s26, v52
	s_mov_b64 s[20:21], 0
